# baseline (speedup 1.0000x reference)
.LBB0_743:
	s_waitcnt vmcnt(0)
	v_mov_b32_e32 v46, v212
	s_lshl_b32 s2, s9, 4
	v_readfirstlane_b32 s0, v46
	s_ashr_i32 s5, s0, 6
	s_ashr_i32 s0, s0, 7
	s_and_b32 s2, s2, 0xffffff80
	s_lshl_b32 s3, s0, 5
	v_and_b32_e32 v219, 31, v46
	s_add_i32 s6, s3, s2
	v_or_b32_e32 v2, s6, v219
	v_ashrrev_i32_e32 v3, 31, v2
	v_readlane_b32 s2, v253, 36
	s_and_b32 s1, s9, 7
	v_lshlrev_b64 v[2:3], 11, v[2:3]
	v_readlane_b32 s3, v253, 37
	s_and_b32 s4, s5, 1
	s_lshl_b32 s42, s1, 8
	v_lshl_add_u64 v[2:3], s[2:3], 0, v[2:3]
	v_bfe_u32 v218, v46, 5, 1
	v_lshl_add_u64 v[2:3], v[2:3], 0, s[42:43]
	s_lshl_b32 s2, s4, 7
	s_mov_b32 s3, s43
	v_lshl_add_u64 v[2:3], v[2:3], 0, s[2:3]
	v_lshlrev_b32_e32 v190, 4, v218
	v_mov_b32_e32 v191, v1
	v_lshl_add_u64 v[2:3], v[2:3], 0, v[190:191]
	global_load_dwordx4 v[160:163], v[2:3], off
	global_load_dwordx4 v[164:167], v[2:3], off offset:32
	global_load_dwordx4 v[34:37], v[2:3], off offset:64
	global_load_dwordx4 v[38:41], v[2:3], off offset:96
	v_ashrrev_i32_e32 v2, 4, v46
	v_ashrrev_i32_e32 v3, 31, v2
	v_readlane_b32 s2, v253, 38
	v_lshlrev_b64 v[4:5], 11, v[2:3]
	v_readlane_b32 s3, v253, 39
	v_bfe_u32 v0, v46, 3, 1
	v_ashrrev_i32_e32 v19, 3, v46
	v_lshl_add_u64 v[4:5], s[2:3], 0, v[4:5]
	s_lshl_b32 s2, s1, 22
	v_readlane_b32 s3, v253, 40
	v_mul_u32_u24_e32 v3, 0x2400, v0
	s_movk_i32 s7, 0x90
	v_lshlrev_b32_e32 v0, 4, v46
	s_add_u32 s2, s3, s2
	v_readlane_b32 s3, v253, 41
	v_lshlrev_b32_e32 v42, 6, v19
	v_and_b32_e32 v48, 15, v46
	v_mul_lo_u32 v2, v2, s7
	v_and_b32_e32 v0, 0x70, v0
	s_addc_u32 s3, s3, 0
	v_ashrrev_i32_e32 v43, 31, v42
	v_lshl_add_u64 v[4:5], v[4:5], 0, s[42:43]
	v_lshlrev_b32_e32 v188, 4, v48
	v_mov_b32_e32 v189, v1
	v_add3_u32 v18, v0, v2, v3
	v_lshl_add_u64 v[2:3], v[42:43], 1, s[2:3]
	s_mul_i32 s2, s4, 0x2400
	v_mad_u32_u24 v47, v219, s7, v190
	v_lshl_add_u64 v[192:193], v[4:5], 0, v[188:189]
	v_add_u32_e32 v20, s2, v47
	s_mov_b32 s2, 0x10000
	v_add_co_u32_e32 v6, vcc, s2, v192
	v_lshl_add_u64 v[194:195], v[2:3], 0, v[0:1]
	global_load_dwordx4 v[2:5], v[192:193], off
	v_addc_co_u32_e32 v7, vcc, 0, v193, vcc
	global_load_dwordx4 v[6:9], v[6:7], off
	s_nop 0
	global_load_dwordx4 v[10:13], v[194:195], off
	v_add_co_u32_e32 v44, vcc, s33, v194
	v_add_u32_e32 v221, 0, v18
	s_nop 0
	v_addc_co_u32_e32 v45, vcc, 0, v195, vcc
	global_load_dwordx4 v[14:17], v[44:45], off
	v_add_co_u32_e32 v26, vcc, 0x20000, v192
	s_nop 1
	v_addc_co_u32_e32 v27, vcc, 0, v193, vcc
	global_load_dwordx4 v[28:31], v[26:27], off
	v_add_co_u32_e32 v26, vcc, 0x30000, v192
	s_nop 1
	v_addc_co_u32_e32 v27, vcc, 0, v193, vcc
	global_load_dwordx4 v[22:25], v[26:27], off
	v_add_u32_e32 v223, 0, v20
	v_and_b32_e32 v217, 63, v46
	v_mov_b64_e32 v[208:209], 0x7ff
	v_mov_b64_e32 v[186:187], 0x800
	s_waitcnt vmcnt(5)
	ds_write_b128 v221, v[2:5]
	s_waitcnt vmcnt(4)
	ds_write_b128 v221, v[6:9] offset:4608
	v_mad_u64_u32 v[2:3], s[2:3], v19, s7, v[0:1]
	s_mov_b32 s2, 0x20000
	v_add_u32_e32 v222, 0, v2
	s_mov_b32 s2, 0x30000
	s_waitcnt vmcnt(3)
	ds_write_b128 v222, v[10:13] offset:55296
	s_waitcnt vmcnt(2)
	ds_write_b128 v222, v[14:17] offset:64512
	s_lshl_b32 s2, s5, 11
	s_add_i32 s2, s2, 0
	s_add_i32 s2, s2, 0x12000
	s_cmp_lt_i32 s5, 4
	s_waitcnt vmcnt(1)
	ds_write_b128 v221, v[28:31] offset:18432
	s_waitcnt vmcnt(0)
	ds_write_b128 v221, v[22:25] offset:23040
	s_waitcnt lgkmcnt(0)
	s_barrier
	ds_read_b128 v[18:21], v223 offset:4608
	ds_read_b128 v[2:5], v223
	ds_read_b128 v[50:53], v223 offset:32
	ds_read_b128 v[54:57], v223 offset:4640
	s_waitcnt lgkmcnt(2)
	v_mfma_f32_32x32x16_bf16 v[2:17], v[2:5], v[160:163], 0
	v_mfma_f32_32x32x16_bf16 v[18:33], v[18:21], v[160:163], 0
	s_waitcnt lgkmcnt(1)
	v_mfma_f32_32x32x16_bf16 v[2:17], v[50:53], v[164:167], v[2:17]
	s_waitcnt lgkmcnt(0)
	v_mfma_f32_32x32x16_bf16 v[18:33], v[54:57], v[164:167], v[18:33]
	ds_read_b128 v[50:53], v223 offset:64
	ds_read_b128 v[54:57], v223 offset:4672
	s_waitcnt lgkmcnt(1)
	v_mfma_f32_32x32x16_bf16 v[2:17], v[50:53], v[34:37], v[2:17]
	s_waitcnt lgkmcnt(0)
	v_mfma_f32_32x32x16_bf16 v[18:33], v[54:57], v[34:37], v[18:33]
	ds_read_b128 v[50:53], v223 offset:96
	ds_read_b128 v[54:57], v223 offset:4704
	s_waitcnt lgkmcnt(1)
	v_mfma_f32_32x32x16_bf16 v[2:17], v[50:53], v[38:41], v[2:17]
	s_waitcnt lgkmcnt(0)
	v_mfma_f32_32x32x16_bf16 v[18:33], v[54:57], v[38:41], v[18:33]
	s_nop 9
	v_max_f32_e32 v49, v3, v3
	v_max_f32_e32 v50, v4, v4
	v_max_f32_e32 v51, v5, v5
	v_max_f32_e32 v0, v19, v19
	v_max_f32_e32 v0, v49, v0
	v_max_f32_e32 v49, v20, v20
	v_max_f32_e32 v49, v50, v49
	v_max_f32_e32 v50, v21, v21
	v_max3_f32 v0, v2, v18, v0
	v_max_f32_e32 v50, v51, v50
	v_max3_f32 v0, v0, v49, v50
	v_max_f32_e32 v49, v22, v22
	v_max_f32_e32 v50, v6, v6
	v_max_f32_e32 v49, v50, v49
	v_max_f32_e32 v50, v23, v23
	v_max_f32_e32 v51, v7, v7
	v_max_f32_e32 v50, v51, v50
	v_max3_f32 v0, v0, v49, v50
	v_max_f32_e32 v49, v24, v24
	v_max_f32_e32 v50, v8, v8
	v_max_f32_e32 v49, v50, v49
	v_max_f32_e32 v50, v25, v25
	v_max_f32_e32 v51, v9, v9
	v_max_f32_e32 v50, v51, v50
	v_max3_f32 v0, v0, v49, v50
	v_max_f32_e32 v49, v26, v26
	v_max_f32_e32 v50, v10, v10
	v_max_f32_e32 v49, v50, v49
	v_max_f32_e32 v50, v27, v27
	v_max_f32_e32 v51, v11, v11
	v_max_f32_e32 v50, v51, v50
	v_max3_f32 v0, v0, v49, v50
	v_max_f32_e32 v49, v28, v28
	v_max_f32_e32 v50, v12, v12
	v_max_f32_e32 v49, v50, v49
	v_max_f32_e32 v50, v29, v29
	v_max_f32_e32 v51, v13, v13
	v_max_f32_e32 v50, v51, v50
	v_max3_f32 v0, v0, v49, v50
	v_max_f32_e32 v49, v30, v30
	v_max_f32_e32 v50, v14, v14
	v_max_f32_e32 v49, v50, v49
	v_max_f32_e32 v50, v31, v31
	v_max_f32_e32 v51, v15, v15
	v_max_f32_e32 v50, v51, v50
	v_max3_f32 v0, v0, v49, v50
	v_max_f32_e32 v49, v32, v32
	v_max_f32_e32 v50, v16, v16
	v_max_f32_e32 v49, v50, v49
	v_max_f32_e32 v50, v33, v33
	v_max_f32_e32 v51, v17, v17
	v_max_f32_e32 v50, v51, v50
	v_max3_f32 v0, v0, v49, v50
	v_and_b32_e32 v50, 64, v215
	v_xor_b32_e32 v49, 32, v215
	v_add_u32_e32 v50, 64, v50
	v_cmp_lt_i32_e32 vcc, v49, v50
	v_lshlrev_b32_e32 v50, 4, v217
	v_add_u32_e32 v224, s2, v50
	v_cndmask_b32_e32 v49, v215, v49, vcc
	ds_write_b128 v224, v[34:37]
	ds_write_b128 v224, v[38:41] offset:1024
	v_add_co_u32_e32 v34, vcc, 0x40000, v192
	v_lshlrev_b32_e32 v189, 2, v49
	s_nop 0
	v_addc_co_u32_e32 v35, vcc, 0, v193, vcc
	global_load_dwordx4 v[128:131], v[34:35], off
	v_add_co_u32_e32 v34, vcc, 0x50000, v192
	ds_bpermute_b32 v49, v189, v0
	s_nop 0
	v_addc_co_u32_e32 v35, vcc, 0, v193, vcc
	global_load_dwordx4 v[144:147], v[34:35], off
	global_load_dwordx4 v[168:171], v[194:195], off
	global_load_dwordx4 v[172:175], v[44:45], off
	s_waitcnt lgkmcnt(0)
	s_barrier
	s_cbranch_scc1 .LBB0_745
	s_setprio 1
